# NSA compressed-pass prologue: two WAW-only vmcnt(0) waits between the three initial tile loads removed (loads overlap), on top of mixB1 conv batching
# speedup vs baseline: 1.0018x; 1.0018x over previous
; #define NSA_GLOAD(R, ti) kv_gload(R, kbase + (size_t)(ti) * 64 * stride, vbase + (size_t)(ti) * 64 * stride, stride)
; template <int MODE> ...
;     ...
;   NSA_NEXT(tcur); NSA_NEXT(t1); NSA_NEXT(t2);
;   if (tcur >= 0) NSA_GLOAD(R0, tcur);
;   if (t1 >= 0) NSA_GLOAD(R1, t1);
;   if (t2 >= 0) NSA_GLOAD(R2, t2);
.LBB0_280:
	s_andn2_b64 vcc, exec, s[78:79]
	s_cbranch_vccnz .LBB0_282
	v_mov_b32 v58, v179
	s_nop 0
	v_ashrrev_i32_e32 v56, 3, v58
	v_ashrrev_i32_e32 v57, 31, v56
	v_lshlrev_b64 v[56:57], 7, v[56:57]
	v_lshlrev_b32_e32 v58, 4, v58
	v_and_b32_e32 v176, 0x70, v58
	v_lshl_add_u64 v[56:57], s[0:1], 0, v[56:57]
	v_lshl_add_u64 v[56:57], v[56:57], 0, v[176:177]
	v_add_co_u32_e32 v58, vcc, 0x2000, v56
	s_nop 1
	v_addc_co_u32_e32 v59, vcc, 0, v57, vcc
	v_add_co_u32_e32 v60, vcc, 0x82000, v56
	s_nop 1
	v_addc_co_u32_e32 v61, vcc, 0, v57, vcc
	global_load_dwordx4 v[56:59], v[58:59], off
	s_nop 0
	global_load_dwordx4 v[60:63], v[60:61], off
.LBB0_282:
	s_andn2_b64 vcc, exec, s[86:87]
	s_cbranch_vccnz .LBB0_284
	v_mov_b32 v66, v179
	s_nop 0
	v_ashrrev_i32_e32 v64, 3, v66
	v_ashrrev_i32_e32 v65, 31, v64
	v_lshlrev_b64 v[64:65], 7, v[64:65]
	v_lshlrev_b32_e32 v66, 4, v66
	v_and_b32_e32 v176, 0x70, v66
	v_lshl_add_u64 v[64:65], s[0:1], 0, v[64:65]
	v_lshl_add_u64 v[64:65], v[64:65], 0, v[176:177]
	v_add_co_u32_e32 v66, vcc, 0x4000, v64
	s_nop 1
	v_addc_co_u32_e32 v67, vcc, 0, v65, vcc
	v_add_co_u32_e32 v68, vcc, 0x84000, v64
	s_nop 1
	v_addc_co_u32_e32 v69, vcc, 0, v65, vcc
	global_load_dwordx4 v[64:67], v[66:67], off
	s_nop 0
	global_load_dwordx4 v[68:71], v[68:69], off
